# v18: P8 LN1 row loop with four rows in flight per wave, hoisted LN weights, DPP reductions
# speedup vs baseline: 1.0096x; 1.0061x over previous
; DI float bflo(unsigned w) { return __uint_as_float(w << 16); }
; DI float bfhi(unsigned w) { return __uint_as_float(w & 0xffff0000u); }
; DI u32x4 pack8(f32x4 a, f32x4 b) { u32x4 w; w.x = pk2(a[0], a[1]); w.y = pk2(a[2], a[3]); w.z = pk2(b[0], b[1]); w.w = pk2(b[2], b[3]); return w; }
; #define REPS(k) for (int rep_ = 0, nrep_ = 1 + ((DUP_MASK >> (k)) & 1); rep_ < nrep_; ++rep_)
; template <bool F32OUT> DI void ln_row_bf16(const bf16_t* z, const float* w, const float* bb, void* o, int lane) {
;     float v[16]; float s = 0.f;
; #pragma unroll
;     for (int j = 0; j < 2; ++j) { const u32x4 p = *(const u32x4*)(z + 512 * j + 8 * lane);
;         v[8 * j + 0] = bflo(p.x); v[8 * j + 1] = bfhi(p.x); v[8 * j + 2] = bflo(p.y); v[8 * j + 3] = bfhi(p.y); v[8 * j + 4] = bflo(p.z); v[8 * j + 5] = bfhi(p.z); v[8 * j + 6] = bflo(p.w); v[8 * j + 7] = bfhi(p.w); }
; #pragma unroll
;     for (int i = 0; i < 16; ++i) s += v[i];
;     const float mean = wave_sum(s) * (1.f / 1024.f); float s2 = 0.f;
; #pragma unroll
;     for (int i = 0; i < 16; ++i) { v[i] -= mean; s2 += v[i] * v[i]; }
;     const float rstd = __builtin_amdgcn_rsqf(wave_sum(s2) * (1.f / 1024.f) + 1e-5f);
; #pragma unroll
;     for (int j = 0; j < 2; ++j) { const int c = 512 * j + 8 * lane; const f32x4 w0 = *(const f32x4*)(w + c), w1 = *(const f32x4*)(w + c + 4), b0 = *(const f32x4*)(bb + c), b1 = *(const f32x4*)(bb + c + 4);
;         f32x4 y0, y1;
; #pragma unroll
;         for (int i = 0; i < 4; ++i) { y0[i] = v[8 * j + i] * rstd * w0[i] + b0[i]; y1[i] = v[8 * j + 4 + i] * rstd * w1[i] + b1[i]; }
;         if (F32OUT) { *(f32x4*)((float*)o + c) = y0; *(f32x4*)((float*)o + c + 4) = y1; }
;         else *(u32x4*)((bf16_t*)o + c) = pack8(y0, y1); }
; }
; __global__ void __launch_bounds__(512, 2) fwd_kernel(Params P) {
;     ...
;     if (IN(8)) REPS(8) { for (int m = gw; m < MT; m += NGW) ln_row_bf16<false>(PROJ + (size_t)m * NPJ + C_Z, P.in[I_LN1W], P.in[I_LN1B], PROJ + (size_t)m * NPJ + C_H, lane); }
.LBB0_1431:
	s_cmp_lt_i32 s90, 9
	s_cselect_b64 s[6:7], -1, 0
	s_and_b64 s[6:7], s[6:7], s[4:5]
	s_andn2_b64 vcc, exec, s[6:7]
	s_cbranch_vccnz .LBB0_1435
	s_cmp_gt_i32 s44, 0x83ff
	s_cbranch_scc1 .LBB0_1435
	s_load_dwordx4 s[8:11], s[0:1], 0x98
	v_lshlrev_b32_e32 v6, 5, v182
	v_lshlrev_b32_e32 v220, 4, v182
	v_mov_b32_e32 v13, 0x3727c5ac
	s_waitcnt lgkmcnt(0)
	global_load_dwordx4 v[130:133], v6, s[8:9]
	global_load_dwordx4 v[134:137], v6, s[8:9] offset:16
	global_load_dwordx4 v[138:141], v6, s[8:9] offset:2048
	global_load_dwordx4 v[142:145], v6, s[8:9] offset:2064
	global_load_dwordx4 v[146:149], v6, s[10:11]
	global_load_dwordx4 v[150:153], v6, s[10:11] offset:16
	global_load_dwordx4 v[154:157], v6, s[10:11] offset:2048
	global_load_dwordx4 v[158:161], v6, s[10:11] offset:2064
	s_mov_b32 s12, s44
	s_add_i32 s13, s12, s46
	s_add_i32 s14, s13, s46
	s_add_i32 s15, s14, s46
	s_lshl_b32 s16, s46, 2
	s_min_i32 s17, s12, 0x83ff
	s_mul_hi_i32 s19, s17, 0x3200
	s_mul_i32 s18, s17, 0x3200
	s_add_u32 s18, s48, s18
	s_addc_u32 s19, s49, s19
	global_load_dwordx4 v[162:165], v220, s[18:19]
	global_load_dwordx4 v[166:169], v220, s[18:19] offset:1024
	s_min_i32 s17, s13, 0x83ff
	s_mul_hi_i32 s19, s17, 0x3200
	s_mul_i32 s18, s17, 0x3200
	s_add_u32 s18, s48, s18
	s_addc_u32 s19, s49, s19
	global_load_dwordx4 v[170:173], v220, s[18:19]
	global_load_dwordx4 v[174:177], v220, s[18:19] offset:1024
	s_min_i32 s17, s14, 0x83ff
	s_mul_hi_i32 s19, s17, 0x3200
	s_mul_i32 s18, s17, 0x3200
	s_add_u32 s18, s48, s18
	s_addc_u32 s19, s49, s19
	global_load_dwordx4 v[222:225], v220, s[18:19]
	global_load_dwordx4 v[226:229], v220, s[18:19] offset:1024
	s_min_i32 s17, s15, 0x83ff
	s_mul_hi_i32 s19, s17, 0x3200
	s_mul_i32 s18, s17, 0x3200
	s_add_u32 s18, s48, s18
	s_addc_u32 s19, s49, s19
	global_load_dwordx4 v[230:233], v220, s[18:19]
	global_load_dwordx4 v[234:237], v220, s[18:19] offset:1024
	s_waitcnt vmcnt(0)
.Lp8ln_loop:
	s_cmp_gt_i32 s12, 0x83ff
	s_cbranch_scc1 .Lp8ln_done
	s_waitcnt vmcnt(12)
	v_lshlrev_b32_e32 v184, 16, v162
	v_and_b32_e32 v185, 0xffff0000, v162
	v_lshlrev_b32_e32 v186, 16, v163
	v_and_b32_e32 v187, 0xffff0000, v163
	v_lshlrev_b32_e32 v188, 16, v164
	v_and_b32_e32 v189, 0xffff0000, v164
	v_lshlrev_b32_e32 v190, 16, v165
	v_and_b32_e32 v191, 0xffff0000, v165
	v_lshlrev_b32_e32 v192, 16, v166
	v_and_b32_e32 v193, 0xffff0000, v166
	v_lshlrev_b32_e32 v194, 16, v167
	v_and_b32_e32 v195, 0xffff0000, v167
	v_lshlrev_b32_e32 v196, 16, v168
	v_and_b32_e32 v197, 0xffff0000, v168
	v_lshlrev_b32_e32 v198, 16, v169
	v_and_b32_e32 v199, 0xffff0000, v169
	v_pk_add_f32 v[200:201], v[184:185], v[186:187]
	v_pk_add_f32 v[202:203], v[188:189], v[190:191]
	v_pk_add_f32 v[204:205], v[192:193], v[194:195]
	v_pk_add_f32 v[206:207], v[196:197], v[198:199]
	v_pk_add_f32 v[200:201], v[200:201], v[202:203]
	v_pk_add_f32 v[204:205], v[204:205], v[206:207]
	v_pk_add_f32 v[200:201], v[200:201], v[204:205]
	s_nop 0
	v_add_f32_e32 v208, v200, v201
	s_nop 1
	v_add_f32_dpp v208, v208, v208 quad_perm:[1,0,3,2] row_mask:0xf bank_mask:0xf
	s_nop 1
	v_add_f32_dpp v208, v208, v208 quad_perm:[2,3,0,1] row_mask:0xf bank_mask:0xf
	s_nop 1
	v_add_f32_dpp v208, v208, v208 row_half_mirror row_mask:0xf bank_mask:0xf
	s_nop 1
	v_add_f32_dpp v208, v208, v208 row_mirror row_mask:0xf bank_mask:0xf
	s_nop 1
	v_add_f32_dpp v208, v208, v208 row_bcast:15 row_mask:0xa bank_mask:0xf
	s_nop 1
	v_add_f32_dpp v208, v208, v208 row_bcast:31 row_mask:0xc bank_mask:0xf
	s_nop 1
	v_readlane_b32 s30, v208, 63
	s_nop 1
	v_mov_b32_e32 v210, s30
	v_mul_f32_e32 v210, 0xba800000, v210
	v_pk_add_f32 v[184:185], v[184:185], v[210:211] op_sel_hi:[1,0]
	v_pk_add_f32 v[186:187], v[186:187], v[210:211] op_sel_hi:[1,0]
	v_pk_add_f32 v[188:189], v[188:189], v[210:211] op_sel_hi:[1,0]
	v_pk_add_f32 v[190:191], v[190:191], v[210:211] op_sel_hi:[1,0]
	v_pk_add_f32 v[192:193], v[192:193], v[210:211] op_sel_hi:[1,0]
	v_pk_add_f32 v[194:195], v[194:195], v[210:211] op_sel_hi:[1,0]
	v_pk_add_f32 v[196:197], v[196:197], v[210:211] op_sel_hi:[1,0]
	v_pk_add_f32 v[198:199], v[198:199], v[210:211] op_sel_hi:[1,0]
	v_pk_mul_f32 v[200:201], v[184:185], v[184:185]
	v_pk_mul_f32 v[202:203], v[192:193], v[192:193]
	v_pk_fma_f32 v[200:201], v[186:187], v[186:187], v[200:201]
	v_pk_fma_f32 v[202:203], v[194:195], v[194:195], v[202:203]
	v_pk_fma_f32 v[200:201], v[188:189], v[188:189], v[200:201]
	v_pk_fma_f32 v[202:203], v[196:197], v[196:197], v[202:203]
	v_pk_fma_f32 v[200:201], v[190:191], v[190:191], v[200:201]
	v_pk_fma_f32 v[202:203], v[198:199], v[198:199], v[202:203]
	v_pk_add_f32 v[200:201], v[200:201], v[202:203]
	s_nop 0
	v_add_f32_e32 v208, v200, v201
	s_nop 1
	v_add_f32_dpp v208, v208, v208 quad_perm:[1,0,3,2] row_mask:0xf bank_mask:0xf
	s_nop 1
	v_add_f32_dpp v208, v208, v208 quad_perm:[2,3,0,1] row_mask:0xf bank_mask:0xf
	s_nop 1
	v_add_f32_dpp v208, v208, v208 row_half_mirror row_mask:0xf bank_mask:0xf
	s_nop 1
	v_add_f32_dpp v208, v208, v208 row_mirror row_mask:0xf bank_mask:0xf
	s_nop 1
	v_add_f32_dpp v208, v208, v208 row_bcast:15 row_mask:0xa bank_mask:0xf
	s_nop 1
	v_add_f32_dpp v208, v208, v208 row_bcast:31 row_mask:0xc bank_mask:0xf
	s_nop 1
	v_readlane_b32 s30, v208, 63
	s_nop 1
	v_mov_b32_e32 v210, s30
	v_fmamk_f32 v210, v210, 0x3a800000, v13
	v_rsq_f32_e32 v210, v210
	s_mul_hi_i32 s19, s12, 0x3200
	s_mul_i32 s18, s12, 0x3200
	s_add_u32 s18, s48, s18
	s_addc_u32 s19, s49, s19
	v_pk_mul_f32 v[184:185], v[184:185], v[210:211] op_sel_hi:[1,0]
	v_pk_mul_f32 v[186:187], v[186:187], v[210:211] op_sel_hi:[1,0]
	v_pk_mul_f32 v[188:189], v[188:189], v[210:211] op_sel_hi:[1,0]
	v_pk_mul_f32 v[190:191], v[190:191], v[210:211] op_sel_hi:[1,0]
; DI u32x4 pack8(f32x4 a, f32x4 b) { u32x4 w; w.x = pk2(a[0], a[1]); w.y = pk2(a[2], a[3]); w.z = pk2(b[0], b[1]); w.w = pk2(b[2], b[3]); return w; }
; #define REPS(k) for (int rep_ = 0, nrep_ = 1 + ((DUP_MASK >> (k)) & 1); rep_ < nrep_; ++rep_)
; template <bool F32OUT> DI void ln_row_bf16(const bf16_t* z, const float* w, const float* bb, void* o, int lane) {
;     ...
;     for (int i = 0; i < 16; ++i) { v[i] -= mean; s2 += v[i] * v[i]; }
;     const float rstd = __builtin_amdgcn_rsqf(wave_sum(s2) * (1.f / 1024.f) + 1e-5f);
; #pragma unroll
;     for (int j = 0; j < 2; ++j) { const int c = 512 * j + 8 * lane; const f32x4 w0 = *(const f32x4*)(w + c), w1 = *(const f32x4*)(w + c + 4), b0 = *(const f32x4*)(bb + c), b1 = *(const f32x4*)(bb + c + 4);
;         f32x4 y0, y1;
; #pragma unroll
;         for (int i = 0; i < 4; ++i) { y0[i] = v[8 * j + i] * rstd * w0[i] + b0[i]; y1[i] = v[8 * j + 4 + i] * rstd * w1[i] + b1[i]; }
;         if (F32OUT) { *(f32x4*)((float*)o + c) = y0; *(f32x4*)((float*)o + c + 4) = y1; }
;         else *(u32x4*)((bf16_t*)o + c) = pack8(y0, y1); }
; }
; __global__ void __launch_bounds__(512, 2) fwd_kernel(Params P) {
;     ...
;     if (IN(8)) REPS(8) { for (int m = gw; m < MT; m += NGW) ln_row_bf16<false>(PROJ + (size_t)m * NPJ + C_Z, P.in[I_LN1W], P.in[I_LN1B], PROJ + (size_t)m * NPJ + C_H, lane); }
	v_pk_mul_f32 v[192:193], v[192:193], v[210:211] op_sel_hi:[1,0]
	v_pk_mul_f32 v[194:195], v[194:195], v[210:211] op_sel_hi:[1,0]
	v_pk_mul_f32 v[196:197], v[196:197], v[210:211] op_sel_hi:[1,0]
	v_pk_mul_f32 v[198:199], v[198:199], v[210:211] op_sel_hi:[1,0]
	v_pk_fma_f32 v[200:201], v[130:131], v[184:185], v[146:147]
	v_pk_fma_f32 v[202:203], v[132:133], v[186:187], v[148:149]
	v_pk_fma_f32 v[204:205], v[134:135], v[188:189], v[150:151]
	v_pk_fma_f32 v[206:207], v[136:137], v[190:191], v[152:153]
	v_cvt_pk_bf16_f32 v212, v200, v201
	v_cvt_pk_bf16_f32 v213, v202, v203
	v_cvt_pk_bf16_f32 v214, v204, v205
	v_cvt_pk_bf16_f32 v215, v206, v207
	global_store_dwordx4 v220, v[212:215], s[18:19] offset:2048
	v_pk_fma_f32 v[200:201], v[138:139], v[192:193], v[154:155]
	v_pk_fma_f32 v[202:203], v[140:141], v[194:195], v[156:157]
	v_pk_fma_f32 v[204:205], v[142:143], v[196:197], v[158:159]
	v_pk_fma_f32 v[206:207], v[144:145], v[198:199], v[160:161]
	v_cvt_pk_bf16_f32 v216, v200, v201
	v_cvt_pk_bf16_f32 v217, v202, v203
	v_cvt_pk_bf16_f32 v218, v204, v205
	v_cvt_pk_bf16_f32 v219, v206, v207
	global_store_dwordx4 v220, v[216:219], s[18:19] offset:3072
	s_add_i32 s12, s12, s16
	s_min_i32 s17, s12, 0x83ff
	s_mul_hi_i32 s19, s17, 0x3200
	s_mul_i32 s18, s17, 0x3200
	s_add_u32 s18, s48, s18
	s_addc_u32 s19, s49, s19
	global_load_dwordx4 v[162:165], v220, s[18:19]
	global_load_dwordx4 v[166:169], v220, s[18:19] offset:1024
	s_cmp_gt_i32 s13, 0x83ff
	s_cbranch_scc1 .Lp8ln_done
	s_waitcnt vmcnt(12)
	v_lshlrev_b32_e32 v184, 16, v170
	v_and_b32_e32 v185, 0xffff0000, v170
	v_lshlrev_b32_e32 v186, 16, v171
	v_and_b32_e32 v187, 0xffff0000, v171
	v_lshlrev_b32_e32 v188, 16, v172
	v_and_b32_e32 v189, 0xffff0000, v172
	v_lshlrev_b32_e32 v190, 16, v173
	v_and_b32_e32 v191, 0xffff0000, v173
	v_lshlrev_b32_e32 v192, 16, v174
	v_and_b32_e32 v193, 0xffff0000, v174
	v_lshlrev_b32_e32 v194, 16, v175
	v_and_b32_e32 v195, 0xffff0000, v175
	v_lshlrev_b32_e32 v196, 16, v176
	v_and_b32_e32 v197, 0xffff0000, v176
	v_lshlrev_b32_e32 v198, 16, v177
	v_and_b32_e32 v199, 0xffff0000, v177
	v_pk_add_f32 v[200:201], v[184:185], v[186:187]
	v_pk_add_f32 v[202:203], v[188:189], v[190:191]
	v_pk_add_f32 v[204:205], v[192:193], v[194:195]
	v_pk_add_f32 v[206:207], v[196:197], v[198:199]
	v_pk_add_f32 v[200:201], v[200:201], v[202:203]
	v_pk_add_f32 v[204:205], v[204:205], v[206:207]
	v_pk_add_f32 v[200:201], v[200:201], v[204:205]
	s_nop 0
	v_add_f32_e32 v208, v200, v201
	s_nop 1
	v_add_f32_dpp v208, v208, v208 quad_perm:[1,0,3,2] row_mask:0xf bank_mask:0xf
	s_nop 1
	v_add_f32_dpp v208, v208, v208 quad_perm:[2,3,0,1] row_mask:0xf bank_mask:0xf
	s_nop 1
	v_add_f32_dpp v208, v208, v208 row_half_mirror row_mask:0xf bank_mask:0xf
	s_nop 1
	v_add_f32_dpp v208, v208, v208 row_mirror row_mask:0xf bank_mask:0xf
	s_nop 1
	v_add_f32_dpp v208, v208, v208 row_bcast:15 row_mask:0xa bank_mask:0xf
	s_nop 1
	v_add_f32_dpp v208, v208, v208 row_bcast:31 row_mask:0xc bank_mask:0xf
	s_nop 1
	v_readlane_b32 s30, v208, 63
	s_nop 1
	v_mov_b32_e32 v210, s30
	v_mul_f32_e32 v210, 0xba800000, v210
	v_pk_add_f32 v[184:185], v[184:185], v[210:211] op_sel_hi:[1,0]
	v_pk_add_f32 v[186:187], v[186:187], v[210:211] op_sel_hi:[1,0]
	v_pk_add_f32 v[188:189], v[188:189], v[210:211] op_sel_hi:[1,0]
	v_pk_add_f32 v[190:191], v[190:191], v[210:211] op_sel_hi:[1,0]
	v_pk_add_f32 v[192:193], v[192:193], v[210:211] op_sel_hi:[1,0]
	v_pk_add_f32 v[194:195], v[194:195], v[210:211] op_sel_hi:[1,0]
	v_pk_add_f32 v[196:197], v[196:197], v[210:211] op_sel_hi:[1,0]
	v_pk_add_f32 v[198:199], v[198:199], v[210:211] op_sel_hi:[1,0]
	v_pk_mul_f32 v[200:201], v[184:185], v[184:185]
	v_pk_mul_f32 v[202:203], v[192:193], v[192:193]
	v_pk_fma_f32 v[200:201], v[186:187], v[186:187], v[200:201]
	v_pk_fma_f32 v[202:203], v[194:195], v[194:195], v[202:203]
	v_pk_fma_f32 v[200:201], v[188:189], v[188:189], v[200:201]
	v_pk_fma_f32 v[202:203], v[196:197], v[196:197], v[202:203]
	v_pk_fma_f32 v[200:201], v[190:191], v[190:191], v[200:201]
	v_pk_fma_f32 v[202:203], v[198:199], v[198:199], v[202:203]
	v_pk_add_f32 v[200:201], v[200:201], v[202:203]
	s_nop 0
	v_add_f32_e32 v208, v200, v201
	s_nop 1
	v_add_f32_dpp v208, v208, v208 quad_perm:[1,0,3,2] row_mask:0xf bank_mask:0xf
	s_nop 1
	v_add_f32_dpp v208, v208, v208 quad_perm:[2,3,0,1] row_mask:0xf bank_mask:0xf
	s_nop 1
	v_add_f32_dpp v208, v208, v208 row_half_mirror row_mask:0xf bank_mask:0xf
	s_nop 1
	v_add_f32_dpp v208, v208, v208 row_mirror row_mask:0xf bank_mask:0xf
	s_nop 1
	v_add_f32_dpp v208, v208, v208 row_bcast:15 row_mask:0xa bank_mask:0xf
	s_nop 1
	v_add_f32_dpp v208, v208, v208 row_bcast:31 row_mask:0xc bank_mask:0xf
	s_nop 1
	v_readlane_b32 s30, v208, 63
	s_nop 1
	v_mov_b32_e32 v210, s30
	v_fmamk_f32 v210, v210, 0x3a800000, v13
	v_rsq_f32_e32 v210, v210
	s_mul_hi_i32 s19, s13, 0x3200
	s_mul_i32 s18, s13, 0x3200
	s_add_u32 s18, s48, s18
	s_addc_u32 s19, s49, s19
	v_pk_mul_f32 v[184:185], v[184:185], v[210:211] op_sel_hi:[1,0]
	v_pk_mul_f32 v[186:187], v[186:187], v[210:211] op_sel_hi:[1,0]
	v_pk_mul_f32 v[188:189], v[188:189], v[210:211] op_sel_hi:[1,0]
	v_pk_mul_f32 v[190:191], v[190:191], v[210:211] op_sel_hi:[1,0]
	v_pk_mul_f32 v[192:193], v[192:193], v[210:211] op_sel_hi:[1,0]
	v_pk_mul_f32 v[194:195], v[194:195], v[210:211] op_sel_hi:[1,0]
	v_pk_mul_f32 v[196:197], v[196:197], v[210:211] op_sel_hi:[1,0]
	v_pk_mul_f32 v[198:199], v[198:199], v[210:211] op_sel_hi:[1,0]
	v_pk_fma_f32 v[200:201], v[130:131], v[184:185], v[146:147]
	v_pk_fma_f32 v[202:203], v[132:133], v[186:187], v[148:149]
	v_pk_fma_f32 v[204:205], v[134:135], v[188:189], v[150:151]
	v_pk_fma_f32 v[206:207], v[136:137], v[190:191], v[152:153]
	v_cvt_pk_bf16_f32 v212, v200, v201
	v_cvt_pk_bf16_f32 v213, v202, v203
	v_cvt_pk_bf16_f32 v214, v204, v205
	v_cvt_pk_bf16_f32 v215, v206, v207
	global_store_dwordx4 v220, v[212:215], s[18:19] offset:2048
	v_pk_fma_f32 v[200:201], v[138:139], v[192:193], v[154:155]
	v_pk_fma_f32 v[202:203], v[140:141], v[194:195], v[156:157]
	v_pk_fma_f32 v[204:205], v[142:143], v[196:197], v[158:159]
	v_pk_fma_f32 v[206:207], v[144:145], v[198:199], v[160:161]
	v_cvt_pk_bf16_f32 v216, v200, v201
	v_cvt_pk_bf16_f32 v217, v202, v203
	v_cvt_pk_bf16_f32 v218, v204, v205
	v_cvt_pk_bf16_f32 v219, v206, v207
	global_store_dwordx4 v220, v[216:219], s[18:19] offset:3072
	s_add_i32 s13, s13, s16
	s_min_i32 s17, s13, 0x83ff
	s_mul_hi_i32 s19, s17, 0x3200
	s_mul_i32 s18, s17, 0x3200
	s_add_u32 s18, s48, s18
	s_addc_u32 s19, s49, s19
	global_load_dwordx4 v[170:173], v220, s[18:19]
	global_load_dwordx4 v[174:177], v220, s[18:19] offset:1024
	s_cmp_gt_i32 s14, 0x83ff
	s_cbranch_scc1 .Lp8ln_done
; DI float bflo(unsigned w) { return __uint_as_float(w << 16); }
; DI float bfhi(unsigned w) { return __uint_as_float(w & 0xffff0000u); }
; DI u32x4 pack8(f32x4 a, f32x4 b) { u32x4 w; w.x = pk2(a[0], a[1]); w.y = pk2(a[2], a[3]); w.z = pk2(b[0], b[1]); w.w = pk2(b[2], b[3]); return w; }
; #define REPS(k) for (int rep_ = 0, nrep_ = 1 + ((DUP_MASK >> (k)) & 1); rep_ < nrep_; ++rep_)
; template <bool F32OUT> DI void ln_row_bf16(const bf16_t* z, const float* w, const float* bb, void* o, int lane) {
;     float v[16]; float s = 0.f;
; #pragma unroll
;     for (int j = 0; j < 2; ++j) { const u32x4 p = *(const u32x4*)(z + 512 * j + 8 * lane);
;         v[8 * j + 0] = bflo(p.x); v[8 * j + 1] = bfhi(p.x); v[8 * j + 2] = bflo(p.y); v[8 * j + 3] = bfhi(p.y); v[8 * j + 4] = bflo(p.z); v[8 * j + 5] = bfhi(p.z); v[8 * j + 6] = bflo(p.w); v[8 * j + 7] = bfhi(p.w); }
; #pragma unroll
;     for (int i = 0; i < 16; ++i) s += v[i];
;     const float mean = wave_sum(s) * (1.f / 1024.f); float s2 = 0.f;
; #pragma unroll
;     for (int i = 0; i < 16; ++i) { v[i] -= mean; s2 += v[i] * v[i]; }
;     const float rstd = __builtin_amdgcn_rsqf(wave_sum(s2) * (1.f / 1024.f) + 1e-5f);
; #pragma unroll
;     for (int j = 0; j < 2; ++j) { const int c = 512 * j + 8 * lane; const f32x4 w0 = *(const f32x4*)(w + c), w1 = *(const f32x4*)(w + c + 4), b0 = *(const f32x4*)(bb + c), b1 = *(const f32x4*)(bb + c + 4);
;         f32x4 y0, y1;
; #pragma unroll
;         for (int i = 0; i < 4; ++i) { y0[i] = v[8 * j + i] * rstd * w0[i] + b0[i]; y1[i] = v[8 * j + 4 + i] * rstd * w1[i] + b1[i]; }
;         if (F32OUT) { *(f32x4*)((float*)o + c) = y0; *(f32x4*)((float*)o + c + 4) = y1; }
;         else *(u32x4*)((bf16_t*)o + c) = pack8(y0, y1); }
; }
; __global__ void __launch_bounds__(512, 2) fwd_kernel(Params P) {
;     ...
;     if (IN(8)) REPS(8) { for (int m = gw; m < MT; m += NGW) ln_row_bf16<false>(PROJ + (size_t)m * NPJ + C_Z, P.in[I_LN1W], P.in[I_LN1B], PROJ + (size_t)m * NPJ + C_H, lane); }
	s_waitcnt vmcnt(12)
	v_lshlrev_b32_e32 v184, 16, v222
	v_and_b32_e32 v185, 0xffff0000, v222
	v_lshlrev_b32_e32 v186, 16, v223
	v_and_b32_e32 v187, 0xffff0000, v223
	v_lshlrev_b32_e32 v188, 16, v224
	v_and_b32_e32 v189, 0xffff0000, v224
	v_lshlrev_b32_e32 v190, 16, v225
	v_and_b32_e32 v191, 0xffff0000, v225
	v_lshlrev_b32_e32 v192, 16, v226
	v_and_b32_e32 v193, 0xffff0000, v226
	v_lshlrev_b32_e32 v194, 16, v227
	v_and_b32_e32 v195, 0xffff0000, v227
	v_lshlrev_b32_e32 v196, 16, v228
	v_and_b32_e32 v197, 0xffff0000, v228
	v_lshlrev_b32_e32 v198, 16, v229
	v_and_b32_e32 v199, 0xffff0000, v229
	v_pk_add_f32 v[200:201], v[184:185], v[186:187]
	v_pk_add_f32 v[202:203], v[188:189], v[190:191]
	v_pk_add_f32 v[204:205], v[192:193], v[194:195]
	v_pk_add_f32 v[206:207], v[196:197], v[198:199]
	v_pk_add_f32 v[200:201], v[200:201], v[202:203]
	v_pk_add_f32 v[204:205], v[204:205], v[206:207]
	v_pk_add_f32 v[200:201], v[200:201], v[204:205]
	s_nop 0
	v_add_f32_e32 v208, v200, v201
	s_nop 1
	v_add_f32_dpp v208, v208, v208 quad_perm:[1,0,3,2] row_mask:0xf bank_mask:0xf
	s_nop 1
	v_add_f32_dpp v208, v208, v208 quad_perm:[2,3,0,1] row_mask:0xf bank_mask:0xf
	s_nop 1
	v_add_f32_dpp v208, v208, v208 row_half_mirror row_mask:0xf bank_mask:0xf
	s_nop 1
	v_add_f32_dpp v208, v208, v208 row_mirror row_mask:0xf bank_mask:0xf
	s_nop 1
	v_add_f32_dpp v208, v208, v208 row_bcast:15 row_mask:0xa bank_mask:0xf
	s_nop 1
	v_add_f32_dpp v208, v208, v208 row_bcast:31 row_mask:0xc bank_mask:0xf
	s_nop 1
	v_readlane_b32 s30, v208, 63
	s_nop 1
	v_mov_b32_e32 v210, s30
	v_mul_f32_e32 v210, 0xba800000, v210
	v_pk_add_f32 v[184:185], v[184:185], v[210:211] op_sel_hi:[1,0]
	v_pk_add_f32 v[186:187], v[186:187], v[210:211] op_sel_hi:[1,0]
	v_pk_add_f32 v[188:189], v[188:189], v[210:211] op_sel_hi:[1,0]
	v_pk_add_f32 v[190:191], v[190:191], v[210:211] op_sel_hi:[1,0]
	v_pk_add_f32 v[192:193], v[192:193], v[210:211] op_sel_hi:[1,0]
	v_pk_add_f32 v[194:195], v[194:195], v[210:211] op_sel_hi:[1,0]
	v_pk_add_f32 v[196:197], v[196:197], v[210:211] op_sel_hi:[1,0]
	v_pk_add_f32 v[198:199], v[198:199], v[210:211] op_sel_hi:[1,0]
	v_pk_mul_f32 v[200:201], v[184:185], v[184:185]
	v_pk_mul_f32 v[202:203], v[192:193], v[192:193]
	v_pk_fma_f32 v[200:201], v[186:187], v[186:187], v[200:201]
	v_pk_fma_f32 v[202:203], v[194:195], v[194:195], v[202:203]
	v_pk_fma_f32 v[200:201], v[188:189], v[188:189], v[200:201]
	v_pk_fma_f32 v[202:203], v[196:197], v[196:197], v[202:203]
	v_pk_fma_f32 v[200:201], v[190:191], v[190:191], v[200:201]
	v_pk_fma_f32 v[202:203], v[198:199], v[198:199], v[202:203]
	v_pk_add_f32 v[200:201], v[200:201], v[202:203]
	s_nop 0
	v_add_f32_e32 v208, v200, v201
	s_nop 1
	v_add_f32_dpp v208, v208, v208 quad_perm:[1,0,3,2] row_mask:0xf bank_mask:0xf
	s_nop 1
	v_add_f32_dpp v208, v208, v208 quad_perm:[2,3,0,1] row_mask:0xf bank_mask:0xf
	s_nop 1
	v_add_f32_dpp v208, v208, v208 row_half_mirror row_mask:0xf bank_mask:0xf
	s_nop 1
	v_add_f32_dpp v208, v208, v208 row_mirror row_mask:0xf bank_mask:0xf
	s_nop 1
	v_add_f32_dpp v208, v208, v208 row_bcast:15 row_mask:0xa bank_mask:0xf
	s_nop 1
	v_add_f32_dpp v208, v208, v208 row_bcast:31 row_mask:0xc bank_mask:0xf
	s_nop 1
	v_readlane_b32 s30, v208, 63
	s_nop 1
	v_mov_b32_e32 v210, s30
	v_fmamk_f32 v210, v210, 0x3a800000, v13
	v_rsq_f32_e32 v210, v210
	s_mul_hi_i32 s19, s14, 0x3200
	s_mul_i32 s18, s14, 0x3200
	s_add_u32 s18, s48, s18
	s_addc_u32 s19, s49, s19
	v_pk_mul_f32 v[184:185], v[184:185], v[210:211] op_sel_hi:[1,0]
	v_pk_mul_f32 v[186:187], v[186:187], v[210:211] op_sel_hi:[1,0]
	v_pk_mul_f32 v[188:189], v[188:189], v[210:211] op_sel_hi:[1,0]
	v_pk_mul_f32 v[190:191], v[190:191], v[210:211] op_sel_hi:[1,0]
	v_pk_mul_f32 v[192:193], v[192:193], v[210:211] op_sel_hi:[1,0]
	v_pk_mul_f32 v[194:195], v[194:195], v[210:211] op_sel_hi:[1,0]
	v_pk_mul_f32 v[196:197], v[196:197], v[210:211] op_sel_hi:[1,0]
	v_pk_mul_f32 v[198:199], v[198:199], v[210:211] op_sel_hi:[1,0]
	v_pk_fma_f32 v[200:201], v[130:131], v[184:185], v[146:147]
	v_pk_fma_f32 v[202:203], v[132:133], v[186:187], v[148:149]
	v_pk_fma_f32 v[204:205], v[134:135], v[188:189], v[150:151]
	v_pk_fma_f32 v[206:207], v[136:137], v[190:191], v[152:153]
	v_cvt_pk_bf16_f32 v212, v200, v201
	v_cvt_pk_bf16_f32 v213, v202, v203
	v_cvt_pk_bf16_f32 v214, v204, v205
	v_cvt_pk_bf16_f32 v215, v206, v207
	global_store_dwordx4 v220, v[212:215], s[18:19] offset:2048
	v_pk_fma_f32 v[200:201], v[138:139], v[192:193], v[154:155]
	v_pk_fma_f32 v[202:203], v[140:141], v[194:195], v[156:157]
	v_pk_fma_f32 v[204:205], v[142:143], v[196:197], v[158:159]
	v_pk_fma_f32 v[206:207], v[144:145], v[198:199], v[160:161]
	v_cvt_pk_bf16_f32 v216, v200, v201
	v_cvt_pk_bf16_f32 v217, v202, v203
	v_cvt_pk_bf16_f32 v218, v204, v205
	v_cvt_pk_bf16_f32 v219, v206, v207
	global_store_dwordx4 v220, v[216:219], s[18:19] offset:3072
	s_add_i32 s14, s14, s16
	s_min_i32 s17, s14, 0x83ff
	s_mul_hi_i32 s19, s17, 0x3200
	s_mul_i32 s18, s17, 0x3200
	s_add_u32 s18, s48, s18
	s_addc_u32 s19, s49, s19
	global_load_dwordx4 v[222:225], v220, s[18:19]
	global_load_dwordx4 v[226:229], v220, s[18:19] offset:1024
	s_cmp_gt_i32 s15, 0x83ff
	s_cbranch_scc1 .Lp8ln_done
; DI u32x4 pack8(f32x4 a, f32x4 b) { u32x4 w; w.x = pk2(a[0], a[1]); w.y = pk2(a[2], a[3]); w.z = pk2(b[0], b[1]); w.w = pk2(b[2], b[3]); return w; }
; __device__ __forceinline__ unsigned xb_ld(unsigned* p)              { return __hip_atomic_load(p, __ATOMIC_RELAXED, __HIP_MEMORY_SCOPE_AGENT); }
; template <bool F32OUT> DI void ln_row_bf16(const bf16_t* z, const float* w, const float* bb, void* o, int lane) {
;     ...
;     for (int i = 0; i < 16; ++i) { v[i] -= mean; s2 += v[i] * v[i]; }
;     const float rstd = __builtin_amdgcn_rsqf(wave_sum(s2) * (1.f / 1024.f) + 1e-5f);
; #pragma unroll
;     for (int j = 0; j < 2; ++j) { const int c = 512 * j + 8 * lane; const f32x4 w0 = *(const f32x4*)(w + c), w1 = *(const f32x4*)(w + c + 4), b0 = *(const f32x4*)(bb + c), b1 = *(const f32x4*)(bb + c + 4);
;         f32x4 y0, y1;
; #pragma unroll
;         for (int i = 0; i < 4; ++i) { y0[i] = v[8 * j + i] * rstd * w0[i] + b0[i]; y1[i] = v[8 * j + 4 + i] * rstd * w1[i] + b1[i]; }
;         if (F32OUT) { *(f32x4*)((float*)o + c) = y0; *(f32x4*)((float*)o + c + 4) = y1; }
;         else *(u32x4*)((bf16_t*)o + c) = pack8(y0, y1); }
; }
; __device__ __forceinline__ void xcd_barrier_complete(unsigned* bar, unsigned x, unsigned& nloc, unsigned& nx) {
;     const unsigned G = gridDim.x * gridDim.y * gridDim.z;
;     unsigned sum, cnt, mine, sp = 0u;
;     for (;;) {
;         sum = 0u; cnt = 0u; mine = 0u;
; #pragma unroll
;         for (unsigned j = 0; j < 16; ++j) { const unsigned c = xb_ld(&bar[XB_XCNT(j)]); sum += c; cnt += (c > 0u) ? 1u : 0u; mine = (j == x) ? c : mine; }
;         if (sum == G) break;
;         __builtin_amdgcn_s_sleep(1);
;         if ((++sp & 255u) == 0u) { if (xb_ld(&bar[XB_TMO])) break; if (sp > XB_SPIN_CAP) { atomicAdd(&bar[XB_TMO], 1u); break; } }
;     }
;     nloc = mine > 0u ? mine : 1u; nx = cnt > 0u ? cnt : 1u;
; }
; __device__ __forceinline__ void xcd_barrier(const XcdBarrier& b) {
;     asm volatile("s_waitcnt vmcnt(0)" ::: "memory");
;     __syncthreads();
;     if (threadIdx.x == 0) {
;         unsigned* bar = b.bar;
;         __builtin_amdgcn_s_waitcnt(0);
;         unsigned nloc = b.st[0], nx = b.st[1];
;         if (nloc == 0u) { xcd_barrier_complete(bar, b.x, nloc, nx); b.st[0] = nloc; b.st[1] = nx; }
	s_waitcnt vmcnt(12)
	v_lshlrev_b32_e32 v184, 16, v230
	v_and_b32_e32 v185, 0xffff0000, v230
	v_lshlrev_b32_e32 v186, 16, v231
	v_and_b32_e32 v187, 0xffff0000, v231
	v_lshlrev_b32_e32 v188, 16, v232
	v_and_b32_e32 v189, 0xffff0000, v232
	v_lshlrev_b32_e32 v190, 16, v233
	v_and_b32_e32 v191, 0xffff0000, v233
	v_lshlrev_b32_e32 v192, 16, v234
	v_and_b32_e32 v193, 0xffff0000, v234
	v_lshlrev_b32_e32 v194, 16, v235
	v_and_b32_e32 v195, 0xffff0000, v235
	v_lshlrev_b32_e32 v196, 16, v236
	v_and_b32_e32 v197, 0xffff0000, v236
	v_lshlrev_b32_e32 v198, 16, v237
	v_and_b32_e32 v199, 0xffff0000, v237
	v_pk_add_f32 v[200:201], v[184:185], v[186:187]
	v_pk_add_f32 v[202:203], v[188:189], v[190:191]
	v_pk_add_f32 v[204:205], v[192:193], v[194:195]
	v_pk_add_f32 v[206:207], v[196:197], v[198:199]
	v_pk_add_f32 v[200:201], v[200:201], v[202:203]
	v_pk_add_f32 v[204:205], v[204:205], v[206:207]
	v_pk_add_f32 v[200:201], v[200:201], v[204:205]
	s_nop 0
	v_add_f32_e32 v208, v200, v201
	s_nop 1
	v_add_f32_dpp v208, v208, v208 quad_perm:[1,0,3,2] row_mask:0xf bank_mask:0xf
	s_nop 1
	v_add_f32_dpp v208, v208, v208 quad_perm:[2,3,0,1] row_mask:0xf bank_mask:0xf
	s_nop 1
	v_add_f32_dpp v208, v208, v208 row_half_mirror row_mask:0xf bank_mask:0xf
	s_nop 1
	v_add_f32_dpp v208, v208, v208 row_mirror row_mask:0xf bank_mask:0xf
	s_nop 1
	v_add_f32_dpp v208, v208, v208 row_bcast:15 row_mask:0xa bank_mask:0xf
	s_nop 1
	v_add_f32_dpp v208, v208, v208 row_bcast:31 row_mask:0xc bank_mask:0xf
	s_nop 1
	v_readlane_b32 s30, v208, 63
	s_nop 1
	v_mov_b32_e32 v210, s30
	v_mul_f32_e32 v210, 0xba800000, v210
	v_pk_add_f32 v[184:185], v[184:185], v[210:211] op_sel_hi:[1,0]
	v_pk_add_f32 v[186:187], v[186:187], v[210:211] op_sel_hi:[1,0]
	v_pk_add_f32 v[188:189], v[188:189], v[210:211] op_sel_hi:[1,0]
	v_pk_add_f32 v[190:191], v[190:191], v[210:211] op_sel_hi:[1,0]
	v_pk_add_f32 v[192:193], v[192:193], v[210:211] op_sel_hi:[1,0]
	v_pk_add_f32 v[194:195], v[194:195], v[210:211] op_sel_hi:[1,0]
	v_pk_add_f32 v[196:197], v[196:197], v[210:211] op_sel_hi:[1,0]
	v_pk_add_f32 v[198:199], v[198:199], v[210:211] op_sel_hi:[1,0]
	v_pk_mul_f32 v[200:201], v[184:185], v[184:185]
	v_pk_mul_f32 v[202:203], v[192:193], v[192:193]
	v_pk_fma_f32 v[200:201], v[186:187], v[186:187], v[200:201]
	v_pk_fma_f32 v[202:203], v[194:195], v[194:195], v[202:203]
	v_pk_fma_f32 v[200:201], v[188:189], v[188:189], v[200:201]
	v_pk_fma_f32 v[202:203], v[196:197], v[196:197], v[202:203]
	v_pk_fma_f32 v[200:201], v[190:191], v[190:191], v[200:201]
	v_pk_fma_f32 v[202:203], v[198:199], v[198:199], v[202:203]
	v_pk_add_f32 v[200:201], v[200:201], v[202:203]
	s_nop 0
	v_add_f32_e32 v208, v200, v201
	s_nop 1
	v_add_f32_dpp v208, v208, v208 quad_perm:[1,0,3,2] row_mask:0xf bank_mask:0xf
	s_nop 1
	v_add_f32_dpp v208, v208, v208 quad_perm:[2,3,0,1] row_mask:0xf bank_mask:0xf
	s_nop 1
	v_add_f32_dpp v208, v208, v208 row_half_mirror row_mask:0xf bank_mask:0xf
	s_nop 1
	v_add_f32_dpp v208, v208, v208 row_mirror row_mask:0xf bank_mask:0xf
	s_nop 1
	v_add_f32_dpp v208, v208, v208 row_bcast:15 row_mask:0xa bank_mask:0xf
	s_nop 1
	v_add_f32_dpp v208, v208, v208 row_bcast:31 row_mask:0xc bank_mask:0xf
	s_nop 1
	v_readlane_b32 s30, v208, 63
	s_nop 1
	v_mov_b32_e32 v210, s30
	v_fmamk_f32 v210, v210, 0x3a800000, v13
	v_rsq_f32_e32 v210, v210
	s_mul_hi_i32 s19, s15, 0x3200
	s_mul_i32 s18, s15, 0x3200
	s_add_u32 s18, s48, s18
	s_addc_u32 s19, s49, s19
	v_pk_mul_f32 v[184:185], v[184:185], v[210:211] op_sel_hi:[1,0]
	v_pk_mul_f32 v[186:187], v[186:187], v[210:211] op_sel_hi:[1,0]
	v_pk_mul_f32 v[188:189], v[188:189], v[210:211] op_sel_hi:[1,0]
	v_pk_mul_f32 v[190:191], v[190:191], v[210:211] op_sel_hi:[1,0]
	v_pk_mul_f32 v[192:193], v[192:193], v[210:211] op_sel_hi:[1,0]
	v_pk_mul_f32 v[194:195], v[194:195], v[210:211] op_sel_hi:[1,0]
	v_pk_mul_f32 v[196:197], v[196:197], v[210:211] op_sel_hi:[1,0]
	v_pk_mul_f32 v[198:199], v[198:199], v[210:211] op_sel_hi:[1,0]
	v_pk_fma_f32 v[200:201], v[130:131], v[184:185], v[146:147]
	v_pk_fma_f32 v[202:203], v[132:133], v[186:187], v[148:149]
	v_pk_fma_f32 v[204:205], v[134:135], v[188:189], v[150:151]
	v_pk_fma_f32 v[206:207], v[136:137], v[190:191], v[152:153]
	v_cvt_pk_bf16_f32 v212, v200, v201
	v_cvt_pk_bf16_f32 v213, v202, v203
	v_cvt_pk_bf16_f32 v214, v204, v205
	v_cvt_pk_bf16_f32 v215, v206, v207
	global_store_dwordx4 v220, v[212:215], s[18:19] offset:2048
	v_pk_fma_f32 v[200:201], v[138:139], v[192:193], v[154:155]
	v_pk_fma_f32 v[202:203], v[140:141], v[194:195], v[156:157]
	v_pk_fma_f32 v[204:205], v[142:143], v[196:197], v[158:159]
	v_pk_fma_f32 v[206:207], v[144:145], v[198:199], v[160:161]
	v_cvt_pk_bf16_f32 v216, v200, v201
	v_cvt_pk_bf16_f32 v217, v202, v203
	v_cvt_pk_bf16_f32 v218, v204, v205
	v_cvt_pk_bf16_f32 v219, v206, v207
	global_store_dwordx4 v220, v[216:219], s[18:19] offset:3072
	s_add_i32 s15, s15, s16
	s_min_i32 s17, s15, 0x83ff
	s_mul_hi_i32 s19, s17, 0x3200
	s_mul_i32 s18, s17, 0x3200
	s_add_u32 s18, s48, s18
	s_addc_u32 s19, s49, s19
	global_load_dwordx4 v[230:233], v220, s[18:19]
	global_load_dwordx4 v[234:237], v220, s[18:19] offset:1024
	s_branch .Lp8ln_loop
.Lp8ln_done:
	s_waitcnt vmcnt(0)
.LBB0_1435:
	s_cmp_gt_i32 s91, 9
	s_cselect_b64 s[4:5], -1, 0
	s_and_b64 s[6:7], s[6:7], s[4:5]
	s_andn2_b64 vcc, exec, s[6:7]
	s_cbranch_vccnz .LBB0_1503
	s_cmp_gt_i32 s90, -1
	s_mov_b64 s[6:7], -1
	s_cbranch_scc0 .LBB0_1490
	s_waitcnt vmcnt(0)
	s_waitcnt vmcnt(0)
	s_barrier
	s_mov_b64 s[6:7], exec
	v_readlane_b32 s8, v242, 0
	v_readlane_b32 s9, v242, 1
	s_and_b64 s[8:9], s[6:7], s[8:9]
	s_mov_b64 exec, s[8:9]
	s_cbranch_execz .LBB0_1489
	s_add_i32 s3, 0, 0x20200
	v_mov_b32_e32 v1, s3
	s_waitcnt vmcnt(0) expcnt(0) lgkmcnt(0)
	ds_read_b32 v3, v1
	s_add_i32 s3, 0, 0x20204
	v_mov_b32_e32 v1, s3
	ds_read_b32 v1, v1
	s_waitcnt lgkmcnt(1)
	v_cmp_ne_u32_e32 vcc, 0, v3
	s_cbranch_vccnz .LBB0_1453
	s_add_u32 s8, s48, 0x1bcc0200
	s_addc_u32 s9, s49, 0
	s_add_u32 s10, s48, 0x1bcc0400
	s_addc_u32 s11, s49, 0
	s_add_u32 s12, s48, 0x1bcc0500
	s_addc_u32 s13, s49, 0
	s_add_u32 s14, s48, 0x1bcc0600
	s_addc_u32 s15, s49, 0
	s_add_u32 s16, s48, 0x1bcc0700
	s_addc_u32 s17, s49, 0
	s_add_u32 s18, s48, 0x1bcc0800
	s_addc_u32 s19, s49, 0
	s_add_u32 s20, s48, 0x1bcc0900
	s_addc_u32 s21, s49, 0
	s_add_u32 s22, s48, 0x1bcc0a00
	s_addc_u32 s23, s49, 0
	s_add_u32 s24, s48, 0x1bcc0b00
	s_addc_u32 s25, s49, 0
	s_add_u32 s26, s48, 0x1bcc0c00
	s_addc_u32 s27, s49, 0
	s_add_u32 s28, s48, 0x1bcc0d00
	s_addc_u32 s29, s49, 0
	s_add_u32 s30, s48, 0x1bcc0e00
	s_addc_u32 s31, s49, 0
	s_add_u32 s34, s48, 0x1bcc0f00
	s_addc_u32 s35, s49, 0
	s_add_u32 s36, s48, 0x1bcc1000
	s_load_dword s3, s[0:1], 0xe8
	s_addc_u32 s37, s49, 0
	s_add_u32 s38, s48, 0x1bcc1100
	s_addc_u32 s39, s49, 0
	s_add_u32 s40, s48, 0x1bcc1200
	s_addc_u32 s41, s49, 0
	s_waitcnt lgkmcnt(0)
	s_mul_i32 s3, s57, s3
	s_add_u32 s52, s48, 0x1bcc1300
	s_mul_i32 s3, s3, s56
	s_addc_u32 s53, s49, 0
	s_mov_b32 s33, 1
	v_mov_b32_e32 v17, 0
	s_branch .LBB0_1441
